# EpiWin rotary-key class: the first row group's body also touches the cos/sin rows of the other seven row groups so their later loads hit cache (was eight serial cold round trips on the two wc==0 waves
# speedup vs baseline: 1.0081x; 1.0081x over previous
.LBB0_657:
	s_andn2_b64 vcc, exec, s[14:15]
	s_cbranch_vccnz .LBB0_660
	s_andn2_b64 vcc, exec, s[86:87]
	s_cbranch_vccnz .LBB0_660
	v_ashrrev_i32_e32 v102, 12, v114
	v_ashrrev_i32_e32 v103, 31, v102
	v_lshl_add_u64 v[98:99], v[124:125], 0, v[160:161]
	v_lshlrev_b64 v[102:103], 15, v[102:103]
	s_movk_i32 s1, 0xfff
	v_lshl_add_u64 v[100:101], v[122:123], 0, v[160:161]
	v_and_or_b32 v96, v114, s1, v102
	global_load_dwordx4 v[114:117], v[98:99], off
	global_load_dwordx4 v[118:121], v[100:101], off
	global_load_dword v254, v[98:99], off offset:1024
	global_load_dword v254, v[100:101], off offset:1024
	global_load_dword v254, v[98:99], off offset:2048
	global_load_dword v254, v[100:101], off offset:2048
	global_load_dword v254, v[98:99], off offset:3072
	global_load_dword v254, v[100:101], off offset:3072
	v_add_co_u32_e32 v252, vcc, 0x2000, v98
	s_nop 1
	v_addc_co_u32_e32 v253, vcc, 0, v99, vcc
	global_load_dword v254, v[252:253], off
	global_load_dword v254, v[252:253], off offset:1024
	global_load_dword v254, v[252:253], off offset:2048
	global_load_dword v254, v[252:253], off offset:3072
	v_add_co_u32_e32 v252, vcc, 0x2000, v100
	s_nop 1
	v_addc_co_u32_e32 v253, vcc, 0, v101, vcc
	global_load_dword v254, v[252:253], off
	global_load_dword v254, v[252:253], off offset:1024
	global_load_dword v254, v[252:253], off offset:2048
	global_load_dword v254, v[252:253], off offset:3072
	v_mov_b64_e32 v[104:105], s[72:73]
	v_mad_u64_u32 v[104:105], s[14:15], v96, s64, v[104:105]
	v_mad_i32_i24 v105, v103, s64, v105
	v_lshl_add_u64 v[102:103], v[144:145], 1, v[104:105]
	s_mov_b32 s1, 0x16920000
	s_waitcnt vmcnt(0)
	v_mov_b32_e32 v96, v117
	v_pk_mul_f32 v[98:99], v[106:107], v[118:119] op_sel:[1,0] op_sel_hi:[0,0]
	v_pk_fma_f32 v[100:101], v[106:107], v[114:115], v[98:99] neg_lo:[0,0,1] neg_hi:[0,0,1]
	v_pk_fma_f32 v[98:99], v[106:107], v[114:115], v[98:99] op_sel_hi:[1,0,1]
	s_nop 0
	v_cvt_pk_bf16_f32 v98, v100, v99
	v_pk_mul_f32 v[100:101], v[108:109], v[118:119] op_sel:[1,1] op_sel_hi:[0,1]
	v_pk_fma_f32 v[104:105], v[108:109], v[114:115], v[100:101] op_sel:[0,1,0] neg_lo:[0,0,1] neg_hi:[0,0,1]
	v_pk_fma_f32 v[100:101], v[108:109], v[114:115], v[100:101] op_sel:[0,1,0]
	s_nop 0
	v_cvt_pk_bf16_f32 v99, v104, v101
	v_pk_mul_f32 v[100:101], v[154:155], v[120:121] op_sel:[1,0] op_sel_hi:[0,0]
	v_pk_fma_f32 v[104:105], v[154:155], v[116:117], v[100:101] neg_lo:[0,0,1] neg_hi:[0,0,1]
	v_pk_fma_f32 v[100:101], v[154:155], v[116:117], v[100:101] op_sel_hi:[1,0,1]
	s_nop 0
	v_cvt_pk_bf16_f32 v100, v104, v101
	v_mov_b32_e32 v104, v121
	v_pk_mul_f32 v[104:105], v[156:157], v[104:105] op_sel:[1,0] op_sel_hi:[0,0]
	v_pk_fma_f32 v[114:115], v[156:157], v[96:97], v[104:105] op_sel_hi:[1,0,1] neg_lo:[0,0,1] neg_hi:[0,0,1]
	v_pk_fma_f32 v[104:105], v[156:157], v[96:97], v[104:105] op_sel_hi:[1,0,1]
	s_nop 0
	v_add_co_u32_e32 v104, vcc, s1, v102
	v_cvt_pk_bf16_f32 v101, v114, v105
	s_nop 0
	v_addc_co_u32_e32 v105, vcc, 0, v103, vcc
	s_mov_b32 s1, 0x169e0000
	global_store_dwordx4 v[104:105], v[98:101], off offset:128
	v_add_co_u32_e32 v104, vcc, s1, v102
	s_mov_b32 s1, 0x16aa0000
	s_nop 0
	v_addc_co_u32_e32 v105, vcc, 0, v103, vcc
	global_store_dwordx4 v[104:105], v[98:101], off offset:128
	v_add_co_u32_e32 v104, vcc, s1, v102
	s_mov_b32 s1, 0x16b60000
	s_nop 0
	v_addc_co_u32_e32 v105, vcc, 0, v103, vcc
	global_store_dwordx4 v[104:105], v[98:101], off offset:128
	v_add_co_u32_e32 v104, vcc, s1, v102
	s_mov_b32 s1, 0x16c20000
	s_nop 0
	v_addc_co_u32_e32 v105, vcc, 0, v103, vcc
	global_store_dwordx4 v[104:105], v[98:101], off offset:128
	v_add_co_u32_e32 v104, vcc, s1, v102
	s_nop 1
	v_addc_co_u32_e32 v105, vcc, 0, v103, vcc
	global_store_dwordx4 v[104:105], v[98:101], off offset:128
	v_add_co_u32_e32 v104, vcc, 0x16ce0000, v102
	s_nop 1
	v_addc_co_u32_e32 v105, vcc, 0, v103, vcc
	global_store_dwordx4 v[104:105], v[98:101], off offset:128
	v_add_co_u32_e32 v104, vcc, 0x16da0000, v102
	s_nop 1
	v_addc_co_u32_e32 v105, vcc, 0, v103, vcc
	v_add_co_u32_e32 v102, vcc, 0x16e60000, v102
	global_store_dwordx4 v[104:105], v[98:101], off offset:128
	s_nop 0
	v_addc_co_u32_e32 v103, vcc, 0, v103, vcc
	global_store_dwordx4 v[102:103], v[98:101], off offset:128

	.amdhsa_kernel _Z10fwd_kernel4Args
		.amdhsa_group_segment_fixed_size 0
		.amdhsa_private_segment_fixed_size 0
		.amdhsa_kernarg_size 480
		.amdhsa_user_sgpr_count 2
		.amdhsa_user_sgpr_dispatch_ptr 0
		.amdhsa_user_sgpr_queue_ptr 0
		.amdhsa_user_sgpr_kernarg_segment_ptr 1
		.amdhsa_user_sgpr_dispatch_id 0
		.amdhsa_user_sgpr_kernarg_preload_length 0
		.amdhsa_user_sgpr_kernarg_preload_offset 0
		.amdhsa_user_sgpr_private_segment_size 0
		.amdhsa_uses_dynamic_stack 0
		.amdhsa_enable_private_segment 0
		.amdhsa_system_sgpr_workgroup_id_x 1
		.amdhsa_system_sgpr_workgroup_id_y 0
		.amdhsa_system_sgpr_workgroup_id_z 0
		.amdhsa_system_sgpr_workgroup_info 0
		.amdhsa_system_vgpr_workitem_id 2
		.amdhsa_next_free_vgpr 256
		.amdhsa_next_free_sgpr 100
		.amdhsa_accum_offset 256
		.amdhsa_reserve_vcc 1
		.amdhsa_float_round_mode_32 0
		.amdhsa_float_round_mode_16_64 0
		.amdhsa_float_denorm_mode_32 3
		.amdhsa_float_denorm_mode_16_64 3
		.amdhsa_dx10_clamp 1
		.amdhsa_ieee_mode 1
		.amdhsa_fp16_overflow 0
		.amdhsa_tg_split 0
		.amdhsa_exception_fp_ieee_invalid_op 0
		.amdhsa_exception_fp_denorm_src 0
		.amdhsa_exception_fp_ieee_div_zero 0
		.amdhsa_exception_fp_ieee_overflow 0
		.amdhsa_exception_fp_ieee_underflow 0
		.amdhsa_exception_fp_ieee_inexact 0
		.amdhsa_exception_int_div_zero 0
	.end_amdhsa_kernel

amdhsa.kernels:
  - .agpr_count:     0
    .args:
      - .offset:         0
        .size:           224
        .value_kind:     by_value
      - .offset:         224
        .size:           4
        .value_kind:     hidden_block_count_x
      - .offset:         228
        .size:           4
        .value_kind:     hidden_block_count_y
      - .offset:         232
        .size:           4
        .value_kind:     hidden_block_count_z
      - .offset:         236
        .size:           2
        .value_kind:     hidden_group_size_x
      - .offset:         238
        .size:           2
        .value_kind:     hidden_group_size_y
      - .offset:         240
        .size:           2
        .value_kind:     hidden_group_size_z
      - .offset:         242
        .size:           2
        .value_kind:     hidden_remainder_x
      - .offset:         244
        .size:           2
        .value_kind:     hidden_remainder_y
      - .offset:         246
        .size:           2
        .value_kind:     hidden_remainder_z
      - .offset:         264
        .size:           8
        .value_kind:     hidden_global_offset_x
      - .offset:         272
        .size:           8
        .value_kind:     hidden_global_offset_y
      - .offset:         280
        .size:           8
        .value_kind:     hidden_global_offset_z
      - .offset:         288
        .size:           2
        .value_kind:     hidden_grid_dims
      - .offset:         312
        .size:           8
        .value_kind:     hidden_multigrid_sync_arg
      - .offset:         344
        .size:           4
        .value_kind:     hidden_dynamic_lds_size
    .group_segment_fixed_size: 0
    .kernarg_segment_align: 8
    .kernarg_segment_size: 480
    .language:       OpenCL C
    .language_version:
      - 2
      - 0
    .max_flat_workgroup_size: 512
    .name:           _Z10fwd_kernel4Args
    .private_segment_fixed_size: 0
    .sgpr_count:     106
    .sgpr_spill_count: 144
    .symbol:         _Z10fwd_kernel4Args.kd
    .uniform_work_group_size: 1
    .uses_dynamic_stack: false
    .vgpr_count:     256
    .vgpr_spill_count: 0
    .wavefront_size: 64
